# attention KV loop: one workgroup barrier per tile (K tile written to LDS before the barrier, V after) instead of two
# speedup vs baseline: 1.0283x; 1.0032x over previous
; __device__ __forceinline__ void partialSM(f32x16& p0, f32x16& p1, float& m_reg, float& mn, float& alpha) {
;     float pmax = p0[0];
; #pragma unroll
;     for (int r = 1; r < 16; ++r) pmax = fmaxf(pmax, p0[r]);
; #pragma unroll
;     for (int r = 0; r < 16; ++r) pmax = fmaxf(pmax, p1[r]);
;     { auto rr = __builtin_amdgcn_permlane32_swap(__float_as_uint(pmax), __float_as_uint(pmax), false, false);
;       pmax = fmaxf(__uint_as_float(rr[0]), __uint_as_float(rr[1])); }
;     constexpr float C2 = 1.4426950408889634f * SCALE;
;     if (__builtin_expect(__all((pmax - m_reg) * SCALE <= THR), 1)) { mn = m_reg; alpha = 1.f; }
;     else { mn = fmaxf(m_reg, pmax); alpha = __builtin_amdgcn_exp2f((m_reg - mn) * C2); m_reg = mn; }
;     const float mnL = -mn * C2;
; #pragma unroll
;     for (int r = 0; r < 16; ++r) p0[r] = fmaf(p0[r], C2, mnL);
; #pragma unroll
;     for (int r = 0; r < 16; ++r) p1[r] = fmaf(p1[r], C2, mnL);
; #pragma unroll
;     for (int r = 0; r < 16; ++r) p0[r] = __builtin_amdgcn_exp2f(p0[r]);
; }
.LBB0_1143:
	v_max_f32_e32 v144, v81, v81
	v_max_f32_e32 v145, v80, v80
	v_max_f32_e32 v144, v145, v144
	v_max3_f32 v144, v144, v82, v83
	v_max3_f32 v144, v144, v84, v85
	v_max3_f32 v144, v144, v86, v87
	v_max3_f32 v144, v144, v88, v89
	v_max3_f32 v144, v144, v90, v91
	v_max3_f32 v144, v144, v92, v93
	v_max3_f32 v144, v144, v94, v95
	v_max3_f32 v144, v144, v64, v65
	v_max3_f32 v144, v144, v66, v67
	v_max3_f32 v144, v144, v68, v69
	v_max3_f32 v144, v144, v70, v71
	v_max3_f32 v144, v144, v72, v73
	v_max3_f32 v144, v144, v74, v75
	v_max3_f32 v144, v144, v76, v77
	v_max3_f32 v144, v144, v78, v79
	v_mov_b32_e32 v145, v144
	s_nop 1
	v_permlane32_swap_b32_e32 v144, v145
	v_max_f32_e32 v145, v145, v145
	v_max_f32_e32 v144, v144, v144
	v_max_f32_e32 v144, v144, v145
	v_max_f32_e32 v146, v152, v152
	v_sub_f32_e32 v145, v144, v152
	v_max_f32_e32 v144, v146, v144
	v_sub_f32_e32 v146, v152, v144
	v_mul_f32_e32 v146, 0x3e0293ee, v146
	v_mul_f32_e32 v145, 0x3db504f3, v145
	v_exp_f32_e32 v146, v146
	v_cmp_ge_f32_e32 vcc, s62, v145
	s_cmp_eq_u64 vcc, exec
	s_cselect_b64 s[8:9], -1, 0
	s_waitcnt vmcnt(0)
	ds_write_b128 v188, v[136:139] offset:32768
	ds_write_b128 v188, v[140:143] offset:40960
	s_waitcnt lgkmcnt(0)
	s_barrier
	s_waitcnt vmcnt(0)
	v_cndmask_b32_e64 v196, v146, 1.0, s[8:9]
	v_cmp_gt_f32_e32 vcc, 1.0, v196
	s_waitcnt vmcnt(3)
	ds_write_b128 v189, v[128:131]
	s_waitcnt vmcnt(2)
	ds_write_b128 v190, v[132:135]
	s_waitcnt vmcnt(1)
	s_waitcnt vmcnt(0)
	s_nop 0
	s_cbranch_vccz .LBB0_1147
	s_and_saveexec_b64 s[58:59], s[6:7]
	ds_write_b32 v179, v196 offset:128
	s_or_b64 exec, exec, s[58:59]
	s_waitcnt lgkmcnt(0)
	ds_read_b128 v[146:149], v178 offset:224
	ds_read_b128 v[154:157], v178 offset:192
	ds_read_b128 v[200:203], v178 offset:160
	ds_read_b128 v[204:207], v178 offset:128
	s_waitcnt lgkmcnt(3)
	v_pk_mul_f32 v[62:63], v[62:63], v[148:149]
	s_waitcnt lgkmcnt(2)
	v_pk_mul_f32 v[58:59], v[58:59], v[156:157]
	s_waitcnt lgkmcnt(1)
	v_pk_mul_f32 v[54:55], v[54:55], v[202:203]
	s_waitcnt lgkmcnt(0)
	v_pk_mul_f32 v[50:51], v[50:51], v[206:207]
	v_pk_mul_f32 v[60:61], v[60:61], v[146:147]
	v_pk_mul_f32 v[56:57], v[56:57], v[154:155]
	v_pk_mul_f32 v[52:53], v[52:53], v[200:201]
	v_pk_mul_f32 v[48:49], v[48:49], v[204:205]
	v_pk_mul_f32 v[46:47], v[46:47], v[148:149]
	v_pk_mul_f32 v[42:43], v[42:43], v[156:157]
	v_pk_mul_f32 v[38:39], v[38:39], v[202:203]
	v_pk_mul_f32 v[34:35], v[34:35], v[206:207]
	v_pk_mul_f32 v[44:45], v[44:45], v[146:147]
	v_pk_mul_f32 v[40:41], v[40:41], v[154:155]
	v_pk_mul_f32 v[36:37], v[36:37], v[200:201]
	v_pk_mul_f32 v[32:33], v[32:33], v[204:205]
	v_pk_mul_f32 v[30:31], v[30:31], v[148:149]
	v_pk_mul_f32 v[26:27], v[26:27], v[156:157]
	v_pk_mul_f32 v[22:23], v[22:23], v[202:203]
	v_pk_mul_f32 v[18:19], v[18:19], v[206:207]
	v_pk_mul_f32 v[28:29], v[28:29], v[146:147]
	v_pk_mul_f32 v[24:25], v[24:25], v[154:155]
	v_pk_mul_f32 v[20:21], v[20:21], v[200:201]
	v_pk_mul_f32 v[16:17], v[16:17], v[204:205]
	v_pk_mul_f32 v[14:15], v[14:15], v[148:149]
	v_pk_mul_f32 v[10:11], v[10:11], v[156:157]
	v_pk_mul_f32 v[6:7], v[6:7], v[202:203]
	v_pk_mul_f32 v[2:3], v[2:3], v[206:207]
	v_pk_mul_f32 v[12:13], v[12:13], v[146:147]
	v_pk_mul_f32 v[8:9], v[8:9], v[154:155]
	v_pk_mul_f32 v[4:5], v[4:5], v[200:201]
	v_pk_mul_f32 v[0:1], v[0:1], v[204:205]
.LBB0_1147:
	v_cndmask_b32_e64 v197, v144, v152, s[8:9]
	v_mul_f32_e32 v199, 0xbe0293ee, v197
	v_fmamk_f32 v80, v80, 0x3e0293ee, v199
	v_fmamk_f32 v81, v81, 0x3e0293ee, v199
	v_fmamk_f32 v82, v82, 0x3e0293ee, v199
	v_fmamk_f32 v83, v83, 0x3e0293ee, v199
	v_fmamk_f32 v84, v84, 0x3e0293ee, v199
	v_fmamk_f32 v85, v85, 0x3e0293ee, v199
	v_fmamk_f32 v86, v86, 0x3e0293ee, v199
	v_fmamk_f32 v87, v87, 0x3e0293ee, v199
	v_fmamk_f32 v88, v88, 0x3e0293ee, v199
	v_fmamk_f32 v89, v89, 0x3e0293ee, v199
	v_fmamk_f32 v90, v90, 0x3e0293ee, v199
	v_fmamk_f32 v91, v91, 0x3e0293ee, v199
	v_fmamk_f32 v92, v92, 0x3e0293ee, v199
	v_fmamk_f32 v93, v93, 0x3e0293ee, v199
	v_fmamk_f32 v94, v94, 0x3e0293ee, v199
	v_fmamk_f32 v95, v95, 0x3e0293ee, v199
	v_exp_f32_e32 v144, v80
	v_exp_f32_e32 v159, v81
	v_exp_f32_e32 v145, v82
	v_exp_f32_e32 v158, v83
	v_exp_f32_e32 v146, v84
	v_exp_f32_e32 v157, v85
	v_exp_f32_e32 v147, v86
	v_exp_f32_e32 v156, v87
	v_exp_f32_e32 v148, v88
	v_exp_f32_e32 v155, v89
	v_exp_f32_e32 v149, v90
	v_exp_f32_e32 v154, v91
	v_exp_f32_e32 v150, v92
	v_exp_f32_e32 v153, v93
	v_exp_f32_e32 v151, v94
	v_exp_f32_e32 v152, v95
	v_fmamk_f32 v208, v64, 0x3e0293ee, v199
	v_fmamk_f32 v207, v75, 0x3e0293ee, v199
	v_fmamk_f32 v209, v65, 0x3e0293ee, v199
	v_fmamk_f32 v210, v66, 0x3e0293ee, v199
	v_fmamk_f32 v211, v67, 0x3e0293ee, v199
	v_fmamk_f32 v212, v68, 0x3e0293ee, v199
	v_fmamk_f32 v201, v69, 0x3e0293ee, v199
	v_fmamk_f32 v202, v70, 0x3e0293ee, v199
	v_fmamk_f32 v203, v71, 0x3e0293ee, v199
	v_fmamk_f32 v204, v72, 0x3e0293ee, v199
	v_fmamk_f32 v205, v73, 0x3e0293ee, v199
	v_fmamk_f32 v206, v74, 0x3e0293ee, v199
	v_fmamk_f32 v200, v76, 0x3e0293ee, v199
	v_fmamk_f32 v213, v77, 0x3e0293ee, v199
	v_fmamk_f32 v214, v78, 0x3e0293ee, v199
	v_fmac_f32_e32 v199, 0x3e0293ee, v79
	s_waitcnt lgkmcnt(0)
	ds_read_b128 v[80:83], v193 offset:256
	ds_read_b128 v[84:87], v193 offset:288
	ds_read_b128 v[64:67], v193 offset:384
	ds_read_b128 v[68:71], v193 offset:416
	ds_read_b128 v[88:91], v193 offset:320
	ds_read_b128 v[72:75], v193 offset:448
	ds_read_b128 v[92:95], v193 offset:352
	ds_read_b128 v[76:79], v193 offset:480
	ds_read_b128 v[216:219], v163 offset:32768
	ds_read_b128 v[220:223], v163 offset:40960
	v_exp_f32_e32 v215, v208
	v_exp_f32_e32 v209, v209
	v_exp_f32_e32 v210, v210
	s_waitcnt lgkmcnt(1)
; __device__ __forceinline__ void finishSM(f32x16& p0, f32x16& p1, float alpha, float& l_reg, bf16x8& pa0, bf16x8& pa1, bf16x8& pa2, bf16x8& pa3) {
; #pragma unroll
;     for (int r = 0; r < 16; ++r) p1[r] = __builtin_amdgcn_exp2f(p1[r]);
;     float ps = 0;
; #pragma unroll
;     for (int r = 0; r < 16; ++r) ps += p0[r];
; #pragma unroll
;     for (int r = 0; r < 16; ++r) ps += p1[r];
;     { auto rr = __builtin_amdgcn_permlane32_swap(__float_as_uint(ps), __float_as_uint(ps), false, false);
;       ps = __uint_as_float(rr[0]) + __uint_as_float(rr[1]); }
;     l_reg = l_reg * alpha + ps;
;     ...
;     PK4(p0, 0, pa0); PK4(p0, 8, pa1); PK4(p1, 0, pa2); PK4(p1, 8, pa3);
; template <int KB>
; __device__ __forceinline__ void qkt(f32x16& p0, f32x16& p1, const char* K_lds, int r32, int hi, const bf16x8* qr, lds_cf bt) {
;     bias_init(p0, p1, bt);
;     const char* kb[4];
; #pragma unroll
;     for (int dd = 0; dd < 4; ++dd) kb[dd] = K_lds + KB * SHM_K + KSWZ(r32, (dd * 16 + hi * 8) * 2);
; #pragma unroll
;     for (int d0 = 0; d0 < 8; ++d0) { const char* a = kb[d0 & 3] + (d0 >> 2) * 128;
;         bf16x8 b0 = *reinterpret_cast<const bf16x8*>(a);
;         bf16x8 b1 = *reinterpret_cast<const bf16x8*>(a + 32 * 256);
;         p0 = __builtin_amdgcn_mfma_f32_32x32x16_bf16(b0, qr[d0], p0, 0, 0, 0);
;         p1 = __builtin_amdgcn_mfma_f32_32x32x16_bf16(b1, qr[d0], p1, 0, 0, 0); }
	v_mfma_f32_32x32x16_bf16 v[80:95], v[216:219], v[112:115], v[80:95]
	v_exp_f32_e32 v211, v211
	v_exp_f32_e32 v212, v212
	v_exp_f32_e32 v201, v201
	v_exp_f32_e32 v202, v202
	v_exp_f32_e32 v203, v203
	v_exp_f32_e32 v204, v204
	v_exp_f32_e32 v205, v205
	s_waitcnt lgkmcnt(0)
	v_mfma_f32_32x32x16_bf16 v[64:79], v[220:223], v[112:115], v[64:79]
	ds_read_b128 v[216:219], v184 offset:32768
	ds_read_b128 v[220:223], v184 offset:40960
	v_exp_f32_e32 v206, v206
	v_exp_f32_e32 v200, v200
	v_exp_f32_e32 v213, v213
	v_exp_f32_e32 v214, v214
	v_exp_f32_e32 v199, v199
	s_waitcnt lgkmcnt(1)
	v_mfma_f32_32x32x16_bf16 v[80:95], v[216:219], v[116:119], v[80:95]
	s_waitcnt lgkmcnt(0)
	v_mfma_f32_32x32x16_bf16 v[64:79], v[220:223], v[116:119], v[64:79]
	ds_read_b128 v[216:219], v185 offset:32768
	ds_read_b128 v[220:223], v185 offset:40960
	s_waitcnt lgkmcnt(1)
	v_mfma_f32_32x32x16_bf16 v[80:95], v[216:219], v[120:123], v[80:95]
	s_waitcnt lgkmcnt(0)
	v_mfma_f32_32x32x16_bf16 v[64:79], v[220:223], v[120:123], v[64:79]
	ds_read_b128 v[216:219], v186 offset:32768
	ds_read_b128 v[220:223], v186 offset:40960
	s_waitcnt lgkmcnt(1)
	v_mfma_f32_32x32x16_bf16 v[80:95], v[216:219], v[124:127], v[80:95]
	s_waitcnt lgkmcnt(0)
	v_mfma_f32_32x32x16_bf16 v[64:79], v[220:223], v[124:127], v[64:79]
	ds_read_b128 v[216:219], v163 offset:32896
	ds_read_b128 v[220:223], v163 offset:41088
	s_waitcnt lgkmcnt(1)
	v_mfma_f32_32x32x16_bf16 v[80:95], v[216:219], v[108:111], v[80:95]
	s_waitcnt lgkmcnt(0)
	v_mfma_f32_32x32x16_bf16 v[64:79], v[220:223], v[108:111], v[64:79]
	ds_read_b128 v[216:219], v184 offset:32896
	ds_read_b128 v[220:223], v184 offset:41088
	s_waitcnt lgkmcnt(1)
	v_mfma_f32_32x32x16_bf16 v[80:95], v[216:219], v[104:107], v[80:95]
	s_waitcnt lgkmcnt(0)
	v_mfma_f32_32x32x16_bf16 v[64:79], v[220:223], v[104:107], v[64:79]
	ds_read_b128 v[216:219], v185 offset:32896
	ds_read_b128 v[220:223], v185 offset:41088
	s_waitcnt lgkmcnt(1)
	v_mfma_f32_32x32x16_bf16 v[80:95], v[216:219], v[100:103], v[80:95]
	s_waitcnt lgkmcnt(0)
	v_mfma_f32_32x32x16_bf16 v[64:79], v[220:223], v[100:103], v[64:79]
	ds_read_b128 v[216:219], v186 offset:32896
	ds_read_b128 v[220:223], v186 offset:41088
	s_waitcnt lgkmcnt(1)
	v_mfma_f32_32x32x16_bf16 v[80:95], v[216:219], v[96:99], v[80:95]
	v_exp_f32_e32 v216, v207
	v_add_f32_e32 v207, 0, v144
	v_add_f32_e32 v207, v159, v207
	v_add_f32_e32 v207, v145, v207
	v_add_f32_e32 v207, v158, v207
	v_add_f32_e32 v207, v146, v207
	v_add_f32_e32 v207, v157, v207
	v_add_f32_e32 v207, v147, v207
	v_add_f32_e32 v207, v156, v207
	v_add_f32_e32 v207, v148, v207
	v_add_f32_e32 v207, v155, v207
	v_add_f32_e32 v207, v149, v207
	v_add_f32_e32 v207, v154, v207
	v_add_f32_e32 v207, v150, v207
	v_add_f32_e32 v207, v153, v207
	v_add_f32_e32 v207, v151, v207
	v_add_f32_e32 v207, v152, v207
	v_add_f32_e32 v207, v215, v207
	v_add_f32_e32 v207, v209, v207
	v_add_f32_e32 v207, v210, v207
	v_add_f32_e32 v207, v211, v207
	v_add_f32_e32 v207, v212, v207
	v_add_f32_e32 v207, v201, v207
	v_add_f32_e32 v207, v202, v207
	v_add_f32_e32 v207, v203, v207
	v_add_f32_e32 v207, v204, v207
	v_add_f32_e32 v207, v205, v207
	s_waitcnt lgkmcnt(0)
	v_mfma_f32_32x32x16_bf16 v[64:79], v[220:223], v[96:99], v[64:79]
	v_add_f32_e32 v207, v206, v207
	v_add_f32_e32 v207, v216, v207
	v_add_f32_e32 v207, v200, v207
	v_add_f32_e32 v207, v213, v207
	v_add_f32_e32 v207, v214, v207
	v_add_f32_e32 v207, v199, v207
	v_mov_b32_e32 v208, v207
	v_cvt_pk_bf16_f32 v144, v144, v159
	v_cvt_pk_bf16_f32 v145, v145, v158
	v_cvt_pk_bf16_f32 v146, v146, v157
	v_cvt_pk_bf16_f32 v147, v147, v156
	v_cvt_pk_bf16_f32 v148, v148, v155
	v_cvt_pk_bf16_f32 v149, v149, v154
	v_cvt_pk_bf16_f32 v150, v150, v153
	v_cvt_pk_bf16_f32 v151, v151, v152
	v_cvt_pk_bf16_f32 v152, v215, v209
	v_cvt_pk_bf16_f32 v153, v210, v211
	v_cvt_pk_bf16_f32 v154, v212, v201
	v_cvt_pk_bf16_f32 v155, v202, v203
	v_cvt_pk_bf16_f32 v156, v204, v205
	v_cvt_pk_bf16_f32 v157, v206, v216
	v_cvt_pk_bf16_f32 v158, v200, v213
	v_cvt_pk_bf16_f32 v159, v214, v199
	s_nop 1
	v_permlane32_swap_b32_e32 v207, v208
	v_permlane32_swap_b32_e32 v144, v146
	v_permlane32_swap_b32_e32 v145, v147
	v_permlane32_swap_b32_e32 v148, v150
	v_permlane32_swap_b32_e32 v149, v151
	v_permlane32_swap_b32_e32 v152, v154
	v_permlane32_swap_b32_e32 v153, v155
	v_permlane32_swap_b32_e32 v156, v158
	v_permlane32_swap_b32_e32 v157, v159
	s_add_i32 s8, s66, 1
	s_cmp_lt_i32 s8, s65
	s_cselect_b64 s[58:59], -1, 0
	s_cmp_ge_i32 s8, s65
	s_cbranch_scc1 .LBB0_1149
	v_add_u32_e32 v128, 0x41, v198
	v_add_u32_e32 v130, 0x61, v198
	v_ashrrev_i32_e32 v129, 31, v128
	v_ashrrev_i32_e32 v131, 31, v130
	v_lshlrev_b64 v[136:137], 8, v[128:129]
	v_lshlrev_b64 v[138:139], 8, v[130:131]
	v_lshl_add_u64 v[128:129], v[164:165], 0, v[136:137]
	v_lshl_add_u64 v[132:133], v[164:165], 0, v[138:139]
	v_lshl_add_u64 v[136:137], v[166:167], 0, v[136:137]
	v_lshl_add_u64 v[140:141], v[166:167], 0, v[138:139]
	global_load_dwordx4 v[128:131], v[128:129], off
	s_nop 0
	global_load_dwordx4 v[132:135], v[132:133], off
	s_nop 0
	global_load_dwordx4 v[136:139], v[136:137], off
	s_nop 0
	global_load_dwordx4 v[140:143], v[140:141], off

; __device__ __forceinline__ void partialSM(f32x16& p0, f32x16& p1, float& m_reg, float& mn, float& alpha) {
;     float pmax = p0[0];
; #pragma unroll
;     for (int r = 1; r < 16; ++r) pmax = fmaxf(pmax, p0[r]);
; #pragma unroll
;     for (int r = 0; r < 16; ++r) pmax = fmaxf(pmax, p1[r]);
;     { auto rr = __builtin_amdgcn_permlane32_swap(__float_as_uint(pmax), __float_as_uint(pmax), false, false);
;       pmax = fmaxf(__uint_as_float(rr[0]), __uint_as_float(rr[1])); }
;     constexpr float C2 = 1.4426950408889634f * SCALE;
;     if (__builtin_expect(__all((pmax - m_reg) * SCALE <= THR), 1)) { mn = m_reg; alpha = 1.f; }
;     else { mn = fmaxf(m_reg, pmax); alpha = __builtin_amdgcn_exp2f((m_reg - mn) * C2); m_reg = mn; }
.LBB0_1151:
	v_max_f32_e32 v144, v81, v81
	v_max_f32_e32 v145, v80, v80
	v_max_f32_e32 v144, v145, v144
	v_max3_f32 v144, v144, v82, v83
	v_max3_f32 v144, v144, v84, v85
	v_max3_f32 v144, v144, v86, v87
	v_max3_f32 v144, v144, v88, v89
	v_max3_f32 v144, v144, v90, v91
	v_max3_f32 v144, v144, v92, v93
	v_max3_f32 v144, v144, v94, v95
	v_max3_f32 v144, v144, v64, v65
	v_max3_f32 v144, v144, v66, v67
	v_max3_f32 v144, v144, v68, v69
	v_max3_f32 v144, v144, v70, v71
	v_max3_f32 v144, v144, v72, v73
	v_max3_f32 v144, v144, v74, v75
	v_max3_f32 v144, v144, v76, v77
	v_max3_f32 v144, v144, v78, v79
	v_mov_b32_e32 v145, v144
	s_nop 1
	v_permlane32_swap_b32_e32 v144, v145
	v_max_f32_e32 v145, v145, v145
	v_max_f32_e32 v144, v144, v144
	v_max_f32_e32 v144, v144, v145
	v_sub_f32_e32 v145, v144, v197
	v_mul_f32_e32 v145, 0x3db504f3, v145
	v_cmp_ge_f32_e32 vcc, s62, v145
	s_cmp_eq_u64 vcc, exec
	s_cselect_b64 s[8:9], -1, 0
	s_andn2_b64 vcc, exec, s[58:59]
	s_cbranch_vccnz .Lfx_skipk
	s_waitcnt vmcnt(0)
	ds_write_b128 v188, v[136:139] offset:49152
	ds_write_b128 v188, v[140:143] offset:57344
	s_waitcnt lgkmcnt(0)
.Lfx_skipk:
	s_barrier
	s_cbranch_vccnz .LBB0_1153
	s_waitcnt vmcnt(0)
	s_waitcnt vmcnt(3)
	ds_write_b128 v189, v[128:131] offset:16384
	s_waitcnt vmcnt(2)
	ds_write_b128 v190, v[132:135] offset:16384

; __device__ __forceinline__ void partialSM(f32x16& p0, f32x16& p1, float& m_reg, float& mn, float& alpha) {
;     ...
;     else { mn = fmaxf(m_reg, pmax); alpha = __builtin_amdgcn_exp2f((m_reg - mn) * C2); m_reg = mn; }
;     const float mnL = -mn * C2;
; #pragma unroll
;     for (int r = 0; r < 16; ++r) p0[r] = fmaf(p0[r], C2, mnL);
; #pragma unroll
;     for (int r = 0; r < 16; ++r) p1[r] = fmaf(p1[r], C2, mnL);
; #pragma unroll
;     for (int r = 0; r < 16; ++r) p0[r] = __builtin_amdgcn_exp2f(p0[r]);
; __device__ __forceinline__ void block(const BlockRef& cur, const BlockRef& nxt, char* lds, Seam& S) {
;     ...
;     for (int t = 1; t + 1 < NT; t += 2) {
;         HALF_STEP(pB0, pB1, mnB, alB, pA0, pA1, alA, t, 1, 0, 0);
;         HALF_STEP(pA0, pA1, mnA, alA, pB0, pB1, alB, t + 1, 0, 1, 1);
;     }
.LBB0_1157:
	v_cndmask_b32_e64 v152, v128, v197, s[8:9]
	v_mul_f32_e32 v128, 0xbe0293ee, v152
	v_mov_b32_e32 v129, v128
	v_fmamk_f32 v80, v80, 0x3e0293ee, v128
	v_fmamk_f32 v81, v81, 0x3e0293ee, v128
	v_fmamk_f32 v82, v82, 0x3e0293ee, v128
	v_fmamk_f32 v83, v83, 0x3e0293ee, v128
	v_fmamk_f32 v84, v84, 0x3e0293ee, v128
	v_fmamk_f32 v85, v85, 0x3e0293ee, v128
	v_fmamk_f32 v86, v86, 0x3e0293ee, v128
	v_fmamk_f32 v87, v87, 0x3e0293ee, v128
	v_fmamk_f32 v88, v88, 0x3e0293ee, v128
	v_fmamk_f32 v89, v89, 0x3e0293ee, v128
	v_fmamk_f32 v90, v90, 0x3e0293ee, v128
	v_fmamk_f32 v91, v91, 0x3e0293ee, v128
	v_fmamk_f32 v92, v92, 0x3e0293ee, v128
	v_fmamk_f32 v93, v93, 0x3e0293ee, v128
	v_fmamk_f32 v94, v94, 0x3e0293ee, v128
	v_fmac_f32_e32 v129, 0x3e0293ee, v95
	v_exp_f32_e32 v204, v80
	v_exp_f32_e32 v206, v81
	v_exp_f32_e32 v202, v82
	v_exp_f32_e32 v205, v83
	v_exp_f32_e32 v201, v84
	v_exp_f32_e32 v203, v85
	v_exp_f32_e32 v199, v86
	v_exp_f32_e32 v200, v87
	v_exp_f32_e32 v157, v88
	v_exp_f32_e32 v197, v89
	v_exp_f32_e32 v155, v90
	v_exp_f32_e32 v158, v91
	v_exp_f32_e32 v154, v92
	v_exp_f32_e32 v198, v93
	v_exp_f32_e32 v156, v94
	v_exp_f32_e32 v159, v129
	v_pk_fma_f32 v[150:151], v[64:65], s[26:27], v[128:129] op_sel_hi:[1,0,0]
	v_add_f32_e32 v64, v194, v195
	v_fmac_f32_e32 v64, v191, v160
	v_add_f32_e32 v160, v207, v208
	s_addk_i32 s67, 0x80
	s_add_i32 s66, s66, 2
	s_waitcnt vmcnt(1)
	v_pk_fma_f32 v[136:137], v[78:79], s[26:27], v[128:129] op_sel_hi:[1,0,0]
	v_pk_fma_f32 v[138:139], v[76:77], s[26:27], v[128:129] op_sel_hi:[1,0,0]
	s_waitcnt vmcnt(0)
	v_pk_fma_f32 v[140:141], v[74:75], s[26:27], v[128:129] op_sel_hi:[1,0,0]
	v_pk_fma_f32 v[142:143], v[72:73], s[26:27], v[128:129] op_sel_hi:[1,0,0]
	v_pk_fma_f32 v[144:145], v[70:71], s[26:27], v[128:129] op_sel_hi:[1,0,0]
	v_pk_fma_f32 v[146:147], v[68:69], s[26:27], v[128:129] op_sel_hi:[1,0,0]
	v_pk_fma_f32 v[148:149], v[66:67], s[26:27], v[128:129] op_sel_hi:[1,0,0]
	v_fmac_f32_e32 v160, v64, v196
	v_add_u32_e32 v192, 0xffffff80, v192
	s_cmp_ge_i32 s66, s65
	v_add_u32_e32 v193, 0x200, v193
	s_waitcnt lgkmcnt(0)
	s_cbranch_scc1 .LBB0_1160
	v_mov_b32_e32 v191, v153
	s_branch .LBB0_1141
